# P5 epilogue: the row block's eight rstd values per lane cached in v236-v243 (recomputed only when the unit's row block changes) instead of reloading SSQ and reducing across lanes in every tile's epilo
# speedup vs baseline: 1.0071x; 1.0071x over previous
; #define PG8_STAGE(bufoff, gbase, voff) do { _Pragma("unroll") for (int _i = 0; _i < 2; ++_i) \
;         __builtin_amdgcn_global_load_lds((const unsigned*)((const char*)(gbase) + (voff)[_i]), (PG8_LAS unsigned*)(lds + (bufoff) + ldsw + _i * 8192), 16, 0, 0); } while (0)
; #define PG8_WAIT_V(n) asm volatile("s_waitcnt vmcnt(" #n ")" ::: "memory")
; #define PG8_BAR __builtin_amdgcn_s_barrier()
; template <class Epi, class Sched, bool ALIGN_EPI = false, bool SP2 = false>
; __device__ __forceinline__ void gemm_phase(PG8_LAS unsigned char* lds, const Gemm g, const Sched& S, const Epi& E) {
;     ...
;     const int tid = tid_, wid = __builtin_amdgcn_readfirstlane(tid >> 6), lane = tid & 63, wr = wid >> 2, wc = wid & 3, fr = lane & 15, fq = lane >> 4;
;     const int K = g.K, nt = K / BK;
;     unsigned voffA[2], voffB[2];
; #pragma unroll
;     for (int i = 0; i < 2; ++i) { int R, C; stage_rc(tid * 16 + i * 8192, R, C); const int Rb = Epi::PERM ? ((R & ~31) + perm32(R & 31)) : R;
;         voffA[i] = (unsigned)(R * g.ld + C) * 2u; voffB[i] = (unsigned)(Rb * g.ld + C) * 2u; }
;     const size_t kstep = (size_t)(BK * 2);
;     const size_t hstep = (size_t)HALF * g.ld * 2; const size_t khb = (size_t)K * 2;
;     const size_t tstep = 2 * hstep;
;     const unsigned ldsw = (unsigned)wid * 1024u;
;     const int aoff = lds_byte(wr * 64 + fr, fq * 8), boff = lds_byte(wc * 32 + fr, fq * 8);
;     ...
;         PG8_STAGE(PG8_SB(1, 0), cB + kstep, voffB); PG8_STAGE(PG8_SA(1, 0), cA + kstep, voffA); PG8_STAGE(PG8_SB(1, 1), cB + hstep + kstep, voffB);
;         PG8_WAIT_V(6); PG8_BAR;
.LBB0_963:
	s_add_u32 s8, s72, 0x4b00000
	s_addc_u32 s9, s73, 0
	s_lshl_b32 s10, s10, 5
	s_and_b32 s15, s10, 0x60
	s_mov_b64 s[10:11], 0x80
	s_add_i32 m0, s39, 0x18000
	v_lshl_add_u64 v[6:7], v[6:7], 0, s[10:11]
	s_lshl_b32 s14, s4, 13
	s_lshl_b32 s16, s15, 7
	s_waitcnt vmcnt(2)
	s_barrier
	global_load_lds_dwordx4 v[6:7], off
	v_lshl_add_u64 v[4:5], v[4:5], 0, s[10:11]
	s_add_i32 m0, s39, 0x1a000
	s_add_i32 s43, s39, 0x8000
	s_add_i32 s44, s39, 0xa000
	global_load_lds_dwordx4 v[4:5], off
	v_lshl_add_u64 v[0:1], v[0:1], 0, s[10:11]
	s_mov_b32 m0, s43
	s_add_u32 s12, s26, 0x40080
	global_load_lds_dwordx4 v[0:1], off
	v_lshl_add_u64 v[0:1], v[2:3], 0, s[10:11]
	s_mov_b32 m0, s44
	s_addc_u32 s13, s27, 0
	global_load_lds_dwordx4 v[0:1], off
	s_add_i32 m0, s39, 0x1c000
	v_lshl_add_u64 v[0:1], s[12:13], 0, v[156:157]
	global_load_lds_dwordx4 v[0:1], off
	v_lshl_add_u64 v[0:1], s[12:13], 0, v[152:153]
	s_add_i32 m0, s39, 0x1e000
	v_bfe_u32 v2, v10, 4, 2
	global_load_lds_dwordx4 v[0:1], off
	v_and_b32_e32 v1, 15, v10
	v_lshlrev_b32_e32 v0, 3, v2
	v_lshlrev_b32_e32 v160, 4, v2
	v_lshlrev_b32_e32 v2, 2, v10
	v_lshl_or_b32 v189, s4, 6, v1
	v_lshl_or_b32 v1, v1, 6, v160
	v_and_b32_e32 v2, 32, v2
	v_bitop3_b32 v4, v1, s14, v2 bitop3:0xde
	v_bitop3_b32 v190, v1, s16, v2 bitop3:0xde
	v_lshlrev_b32_e32 v1, 14, v13
	s_sext_i32_i16 s23, s2
	s_cmpk_lt_u32 s3, 0x100
	v_lshl_add_u64 v[2:3], s[72:73], 0, v[160:161]
	s_mov_b64 s[2:3], 0x100000
	v_and_b32_e32 v1, 0xffff8000, v1
	v_lshl_add_u64 v[162:163], v[2:3], 0, s[2:3]
	v_lshl_add_u32 v1, v12, 11, v1
	v_and_b32_e32 v2, 1, v13
	v_lshl_or_b32 v1, v2, 6, v1
	v_lshl_add_u32 v164, v14, 1, v1
	v_lshlrev_b32_e32 v1, 14, v8
	v_and_b32_e32 v1, 0xffff8000, v1
	v_lshl_add_u32 v1, v9, 11, v1
	v_and_b32_e32 v2, 1, v8
	s_waitcnt vmcnt(6)
	v_lshl_or_b32 v1, v2, 6, v1
	s_cselect_b64 s[12:13], -1, 0
	v_lshl_add_u32 v166, v11, 1, v1
	s_add_i32 s47, 0, 0x10000
	s_add_i32 s48, 0, 0x14000
	v_mbcnt_lo_u32_b32 v1, -1, 0
	s_ashr_i32 s45, s84, 31
	s_mov_b32 s46, s84
	v_mov_b32_e32 v165, v161
	v_mov_b32_e32 v167, v161
	v_mov_b64_e32 v[168:169], 0x580
	v_mov_b64_e32 v[170:171], 0x57f
	v_add_u32_e32 v191, s47, v190
	v_add_u32_e32 v192, s48, v190
	v_add_u32_e32 v193, 0, v4
	v_mbcnt_hi_u32_b32 v194, -1, v1
	v_mov_b32_e32 v195, 0x358637bd
	s_movk_i32 s49, 0x1600
	s_lshl_b32 s4, s15, 1
	v_lshlrev_b32_e32 v160, 1, v0
	s_mov_b32 s100, -1
	s_mov_b32 s50, s5
	s_barrier
	s_branch .LBB0_966

;     __device__ __forceinline__ void operator()(const f32x4 (&acc)[2][2][4][2], const Unit& u, int wr, int wc, int fr, int fq) const {
;         const int row0 = u.pm * BM + wr * 64 + fr;
;         f32x4 sq[2][4];
; #pragma unroll
;         for (int ai = 0; ai < 2; ++ai)
; #pragma unroll
;             for (int m = 0; m < 4; ++m) sq[ai][m] = *(const f32x4*)(SSQ + (size_t)(row0 + ai * HALF + m * 16) * 16 + 4 * fq);
; #pragma unroll
;         for (int ai = 0; ai < 2; ++ai)
; #pragma unroll
;             for (int m = 0; m < 4; ++m) {
;                 const int row = row0 + ai * HALF + m * 16;
;                 float ss = (sq[ai][m][0] + sq[ai][m][1]) + (sq[ai][m][2] + sq[ai][m][3]);
;                 ss += __shfl_xor(ss, 16); ss += __shfl_xor(ss, 32);
;                 const float rstd = __builtin_amdgcn_rsqf(ss * (1.0f / 1024.0f) + 1e-6f);
.LBB0_972:
	s_cmp_eq_u32 s22, s100
	s_cbranch_scc1 .Lmy_ssq_have
	s_mov_b32 s100, s22
	v_lshl_add_u32 v244, s22, 8, v189
	v_xor_b32_e32 v252, 16, v194
	v_xor_b32_e32 v253, 32, v194
	v_lshlrev_b32_e32 v252, 2, v252
	v_lshlrev_b32_e32 v253, 2, v253
	v_add_u32_e32 v250, 0, v244
	v_mov_b32_e32 v251, 0
	v_lshlrev_b64 v[250:251], 6, v[250:251]
	v_lshl_add_u64 v[250:251], v[162:163], 0, v[250:251]
	global_load_dwordx4 v[220:223], v[250:251], off
	v_add_u32_e32 v250, 16, v244
	v_mov_b32_e32 v251, 0
	v_lshlrev_b64 v[250:251], 6, v[250:251]
	v_lshl_add_u64 v[250:251], v[162:163], 0, v[250:251]
	global_load_dwordx4 v[224:227], v[250:251], off
	v_add_u32_e32 v250, 32, v244
	v_mov_b32_e32 v251, 0
	v_lshlrev_b64 v[250:251], 6, v[250:251]
	v_lshl_add_u64 v[250:251], v[162:163], 0, v[250:251]
	global_load_dwordx4 v[228:231], v[250:251], off
	v_add_u32_e32 v250, 48, v244
	v_mov_b32_e32 v251, 0
	v_lshlrev_b64 v[250:251], 6, v[250:251]
	v_lshl_add_u64 v[250:251], v[162:163], 0, v[250:251]
	global_load_dwordx4 v[232:235], v[250:251], off
	s_waitcnt vmcnt(3)
	v_add_f32_e32 v220, v220, v221
	v_add_f32_e32 v222, v222, v223
	v_add_f32_e32 v220, v220, v222
	ds_bpermute_b32 v221, v252, v220
	s_waitcnt vmcnt(2)
	v_add_f32_e32 v224, v224, v225
	v_add_f32_e32 v226, v226, v227
	v_add_f32_e32 v224, v224, v226
	ds_bpermute_b32 v225, v252, v224
	s_waitcnt vmcnt(1)
	v_add_f32_e32 v228, v228, v229
	v_add_f32_e32 v230, v230, v231
	v_add_f32_e32 v228, v228, v230
	ds_bpermute_b32 v229, v252, v228
	s_waitcnt vmcnt(0)
	v_add_f32_e32 v232, v232, v233
	v_add_f32_e32 v234, v234, v235
	v_add_f32_e32 v232, v232, v234
	ds_bpermute_b32 v233, v252, v232
	s_waitcnt lgkmcnt(3)
	v_add_f32_e32 v220, v220, v221
	s_waitcnt lgkmcnt(2)
	v_add_f32_e32 v224, v224, v225
	s_waitcnt lgkmcnt(1)
	v_add_f32_e32 v228, v228, v229
	s_waitcnt lgkmcnt(0)
	v_add_f32_e32 v232, v232, v233
	ds_bpermute_b32 v221, v253, v220
	ds_bpermute_b32 v225, v253, v224
	ds_bpermute_b32 v229, v253, v228
	ds_bpermute_b32 v233, v253, v232
	s_waitcnt lgkmcnt(3)
	v_add_f32_e32 v220, v220, v221
	v_fmamk_f32 v220, v220, 0x3a800000, v195
	v_rsq_f32_e32 v236, v220
	s_waitcnt lgkmcnt(2)
	v_add_f32_e32 v224, v224, v225
	v_fmamk_f32 v224, v224, 0x3a800000, v195
	v_rsq_f32_e32 v237, v224
	s_waitcnt lgkmcnt(1)
	v_add_f32_e32 v228, v228, v229
	v_fmamk_f32 v228, v228, 0x3a800000, v195
	v_rsq_f32_e32 v238, v228
	s_waitcnt lgkmcnt(0)
	v_add_f32_e32 v232, v232, v233
	v_fmamk_f32 v232, v232, 0x3a800000, v195
	v_rsq_f32_e32 v239, v232
	v_add_u32_e32 v250, 128, v244
	v_mov_b32_e32 v251, 0
	v_lshlrev_b64 v[250:251], 6, v[250:251]
	v_lshl_add_u64 v[250:251], v[162:163], 0, v[250:251]
	global_load_dwordx4 v[220:223], v[250:251], off
	v_add_u32_e32 v250, 144, v244
	v_mov_b32_e32 v251, 0
	v_lshlrev_b64 v[250:251], 6, v[250:251]
	v_lshl_add_u64 v[250:251], v[162:163], 0, v[250:251]
	global_load_dwordx4 v[224:227], v[250:251], off
	v_add_u32_e32 v250, 160, v244
	v_mov_b32_e32 v251, 0
	v_lshlrev_b64 v[250:251], 6, v[250:251]
	v_lshl_add_u64 v[250:251], v[162:163], 0, v[250:251]
	global_load_dwordx4 v[228:231], v[250:251], off
	v_add_u32_e32 v250, 176, v244
	v_mov_b32_e32 v251, 0
	v_lshlrev_b64 v[250:251], 6, v[250:251]
	v_lshl_add_u64 v[250:251], v[162:163], 0, v[250:251]
	global_load_dwordx4 v[232:235], v[250:251], off
	s_waitcnt vmcnt(3)
	v_add_f32_e32 v220, v220, v221
	v_add_f32_e32 v222, v222, v223
	v_add_f32_e32 v220, v220, v222
	ds_bpermute_b32 v221, v252, v220
	s_waitcnt vmcnt(2)
	v_add_f32_e32 v224, v224, v225
	v_add_f32_e32 v226, v226, v227
	v_add_f32_e32 v224, v224, v226
	ds_bpermute_b32 v225, v252, v224
	s_waitcnt vmcnt(1)
	v_add_f32_e32 v228, v228, v229
	v_add_f32_e32 v230, v230, v231
	v_add_f32_e32 v228, v228, v230
	ds_bpermute_b32 v229, v252, v228
	s_waitcnt vmcnt(0)
	v_add_f32_e32 v232, v232, v233
	v_add_f32_e32 v234, v234, v235
	v_add_f32_e32 v232, v232, v234
	ds_bpermute_b32 v233, v252, v232
	s_waitcnt lgkmcnt(3)
	v_add_f32_e32 v220, v220, v221
	s_waitcnt lgkmcnt(2)
	v_add_f32_e32 v224, v224, v225
	s_waitcnt lgkmcnt(1)
	v_add_f32_e32 v228, v228, v229
	s_waitcnt lgkmcnt(0)
	v_add_f32_e32 v232, v232, v233
	ds_bpermute_b32 v221, v253, v220
	ds_bpermute_b32 v225, v253, v224
	ds_bpermute_b32 v229, v253, v228
	ds_bpermute_b32 v233, v253, v232
	s_waitcnt lgkmcnt(3)
	v_add_f32_e32 v220, v220, v221
	v_fmamk_f32 v220, v220, 0x3a800000, v195
	v_rsq_f32_e32 v240, v220
	s_waitcnt lgkmcnt(2)
	v_add_f32_e32 v224, v224, v225
	v_fmamk_f32 v224, v224, 0x3a800000, v195
	v_rsq_f32_e32 v241, v224
	s_waitcnt lgkmcnt(1)
	v_add_f32_e32 v228, v228, v229
	v_fmamk_f32 v228, v228, 0x3a800000, v195
	v_rsq_f32_e32 v242, v228
	s_waitcnt lgkmcnt(0)
	v_add_f32_e32 v232, v232, v233
	v_fmamk_f32 v232, v232, 0x3a800000, v195
	v_rsq_f32_e32 v243, v232
; __device__ __forceinline__ float sigm(float x) { return __builtin_amdgcn_rcpf(1.0f + __expf(-x)); }
; __device__ __forceinline__ u32x4 pack8_bf16(const float (&o)[8]) { u32x4 w; w.x = cvt_pk_bf16(o[0], o[1]); w.y = cvt_pk_bf16(o[2], o[3]); w.z = cvt_pk_bf16(o[4], o[5]); w.w = cvt_pk_bf16(o[6], o[7]); return w; }
;     __device__ __forceinline__ void operator()(const f32x4 (&acc)[2][2][4][2], const Unit& u, int wr, int wc, int fr, int fq) const {
;     ...
;         for (int ai = 0; ai < 2; ++ai)
; #pragma unroll
;             for (int m = 0; m < 4; ++m) {
;                 const int row = row0 + ai * HALF + m * 16;
;                 float ss = (sq[ai][m][0] + sq[ai][m][1]) + (sq[ai][m][2] + sq[ai][m][3]);
;                 ss += __shfl_xor(ss, 16); ss += __shfl_xor(ss, 32);
;                 const float rstd = __builtin_amdgcn_rsqf(ss * (1.0f / 1024.0f) + 1e-6f);
;                 float o[8];
; #pragma unroll
;                 for (int k = 0; k < 8; ++k) { const float g = acc[ai][0][m][k >> 2][k & 3] * rstd, up = acc[ai][1][m][k >> 2][k & 3] * rstd; o[k] = g * sigm(g) * up; }
;                 *(u32x4*)(ACT + (size_t)row * 2816 + u.pn * 128 + wc * 32 + 8 * fq) = pack8_bf16(o);
;             }
.Lmy_ssq_have:
	v_lshl_add_u32 v186, s22, 8, v189
	v_ashrrev_i32_e32 v187, 31, v186
	v_lshlrev_b64 v[128:129], 6, v[186:187]
	v_lshl_add_u64 v[128:129], v[162:163], 0, v[128:129]
	v_or_b32_e32 v184, 16, v186
	v_ashrrev_i32_e32 v185, 31, v184
	v_lshlrev_b64 v[132:133], 6, v[184:185]
	v_lshl_add_u64 v[132:133], v[162:163], 0, v[132:133]
	v_or_b32_e32 v182, 32, v186
	v_add_u32_e32 v178, 0x80, v186
	v_add_u32_e32 v176, 0x90, v186
	v_add_u32_e32 v174, 0xa0, v186
	v_or_b32_e32 v180, 48, v186
	v_add_u32_e32 v172, 0xb0, v186
	v_ashrrev_i32_e32 v183, 31, v182
	v_ashrrev_i32_e32 v179, 31, v178
	v_ashrrev_i32_e32 v177, 31, v176
	v_ashrrev_i32_e32 v175, 31, v174
	v_ashrrev_i32_e32 v181, 31, v180
	v_ashrrev_i32_e32 v173, 31, v172
	v_lshlrev_b64 v[132:133], 6, v[182:183]
	v_lshlrev_b64 v[136:137], 6, v[178:179]
	v_lshlrev_b64 v[138:139], 6, v[176:177]
	v_lshlrev_b64 v[140:141], 6, v[174:175]
	v_lshlrev_b64 v[134:135], 6, v[180:181]
	v_lshlrev_b64 v[142:143], 6, v[172:173]
	v_lshl_add_u64 v[132:133], v[162:163], 0, v[132:133]
	v_lshl_add_u64 v[136:137], v[162:163], 0, v[136:137]
	v_lshl_add_u64 v[138:139], v[162:163], 0, v[138:139]
	v_lshl_add_u64 v[200:201], v[162:163], 0, v[140:141]
	v_lshl_add_u64 v[134:135], v[162:163], 0, v[134:135]
	v_lshl_add_u64 v[202:203], v[162:163], 0, v[142:143]
	s_lshl_b32 s22, s23, 7
	s_ashr_i32 s23, s22, 31
	s_lshl_b64 s[22:23], s[22:23], 1
	s_andn2_b64 vcc, exec, s[2:3]
	s_mov_b64 s[2:3], -1
	s_nop 0
	v_mov_b32_e32 v198, v236
	v_pk_mul_f32 v[124:125], v[124:125], v[198:199] op_sel_hi:[1,0]
	v_pk_mul_f32 v[120:121], v[120:121], v[198:199] op_sel_hi:[1,0]
	v_pk_mul_f32 v[122:123], v[122:123], v[198:199] op_sel_hi:[1,0]
	v_pk_mul_f32 v[116:117], v[116:117], v[198:199] op_sel_hi:[1,0]
	v_pk_mul_f32 v[126:127], v[126:127], v[198:199] op_sel_hi:[1,0]
	v_pk_mul_f32 v[118:119], v[118:119], v[198:199] op_sel_hi:[1,0]
	v_pk_mul_f32 v[112:113], v[112:113], v[198:199] op_sel_hi:[1,0]
	v_pk_mul_f32 v[114:115], v[114:115], v[198:199] op_sel_hi:[1,0]
	v_mul_f32_e32 v181, 0xbfb8aa3b, v124
	v_mul_f32_e32 v183, 0xbfb8aa3b, v125
	v_mul_f32_e32 v196, 0xbfb8aa3b, v120
	v_mul_f32_e32 v197, 0xbfb8aa3b, v121
	v_mul_f32_e32 v198, 0xbfb8aa3b, v122
	v_mul_f32_e32 v199, 0xbfb8aa3b, v123
	v_exp_f32_e32 v181, v181
	v_exp_f32_e32 v183, v183
	v_exp_f32_e32 v196, v196
	v_exp_f32_e32 v197, v197
	v_exp_f32_e32 v198, v198
	v_exp_f32_e32 v199, v199
	v_add_f32_e32 v181, 1.0, v181
	v_add_f32_e32 v183, 1.0, v183
	v_add_f32_e32 v200, 1.0, v196
	v_add_f32_e32 v201, 1.0, v197
	v_add_f32_e32 v202, 1.0, v198
	v_add_f32_e32 v203, 1.0, v199
	v_rcp_f32_e32 v196, v181
	v_rcp_f32_e32 v197, v183
	v_rcp_f32_e32 v200, v200
	v_rcp_f32_e32 v201, v201
	v_rcp_f32_e32 v202, v202
	v_rcp_f32_e32 v203, v203
	v_pk_mul_f32 v[124:125], v[124:125], v[196:197]
	v_pk_mul_f32 v[120:121], v[120:121], v[200:201]
	v_pk_mul_f32 v[122:123], v[122:123], v[202:203]
	v_pk_mul_f32 v[116:117], v[116:117], v[124:125]
	v_pk_mul_f32 v[112:113], v[112:113], v[120:121]
	v_pk_mul_f32 v[120:121], v[114:115], v[122:123]
	v_cvt_pk_bf16_f32 v114, v116, v117
	v_cvt_pk_bf16_f32 v117, v120, v121
	v_mul_f32_e32 v185, 0xbfb8aa3b, v126
	v_mul_f32_e32 v187, 0xbfb8aa3b, v127
	v_exp_f32_e32 v185, v185
	v_exp_f32_e32 v187, v187
	v_add_f32_e32 v185, 1.0, v185
	v_add_f32_e32 v187, 1.0, v187
	v_rcp_f32_e32 v198, v185
	v_rcp_f32_e32 v199, v187
	v_mov_b32_e32 v120, v237
	v_cvt_pk_bf16_f32 v116, v112, v113
	v_mov_b64_e32 v[112:113], s[8:9]
	v_pk_mul_f32 v[126:127], v[126:127], v[198:199]
	v_pk_mul_f32 v[108:109], v[108:109], v[120:121] op_sel_hi:[1,0]
	v_pk_mul_f32 v[118:119], v[118:119], v[126:127]
	v_mul_f32_e32 v121, 0xbfb8aa3b, v108
	v_cvt_pk_bf16_f32 v115, v118, v119
	v_mad_i64_i32 v[118:119], s[24:25], v186, s49, v[112:113]
	v_exp_f32_e32 v121, v121
	v_lshl_add_u64 v[118:119], v[118:119], 0, s[22:23]
	v_lshl_add_u64 v[118:119], v[118:119], 0, s[4:5]
	v_lshl_add_u64 v[118:119], v[118:119], 0, v[160:161]
	global_store_dwordx4 v[118:119], v[114:117], off
	v_pk_mul_f32 v[110:111], v[110:111], v[120:121] op_sel_hi:[1,0]
	v_pk_mul_f32 v[100:101], v[100:101], v[120:121] op_sel_hi:[1,0]
	v_mul_f32_e32 v114, 0xbfb8aa3b, v109
	v_exp_f32_e32 v115, v114
	v_mul_f32_e32 v116, 0xbfb8aa3b, v110
	v_mul_f32_e32 v117, 0xbfb8aa3b, v111
	v_exp_f32_e32 v116, v116
	v_exp_f32_e32 v117, v117
	v_add_f32_e32 v114, 1.0, v121
	v_add_f32_e32 v115, 1.0, v115
	v_rcp_f32_e32 v114, v114
	v_rcp_f32_e32 v115, v115
	v_add_f32_e32 v116, 1.0, v116
	v_add_f32_e32 v117, 1.0, v117
	v_rcp_f32_e32 v116, v116
	v_rcp_f32_e32 v117, v117
	v_pk_mul_f32 v[108:109], v[108:109], v[114:115]
	v_pk_mul_f32 v[102:103], v[102:103], v[120:121] op_sel_hi:[1,0]
	v_pk_mul_f32 v[100:101], v[100:101], v[108:109]
	v_pk_mul_f32 v[108:109], v[110:111], v[116:117]
	v_pk_mul_f32 v[104:105], v[104:105], v[120:121] op_sel_hi:[1,0]
	v_pk_mul_f32 v[102:103], v[102:103], v[108:109]
	v_mul_f32_e32 v110, 0xbfb8aa3b, v104
	v_mul_f32_e32 v108, 0xbfb8aa3b, v105
	v_exp_f32_e32 v110, v110
	v_exp_f32_e32 v109, v108
	v_pk_mul_f32 v[106:107], v[106:107], v[120:121] op_sel_hi:[1,0]
	v_pk_mul_f32 v[96:97], v[96:97], v[120:121] op_sel_hi:[1,0]
	v_add_f32_e32 v108, 1.0, v110
	v_add_f32_e32 v109, 1.0, v109
	v_mul_f32_e32 v110, 0xbfb8aa3b, v106
	v_mul_f32_e32 v111, 0xbfb8aa3b, v107
	v_rcp_f32_e32 v108, v108
	v_rcp_f32_e32 v109, v109
	v_exp_f32_e32 v110, v110
	v_exp_f32_e32 v111, v111
	v_pk_mul_f32 v[104:105], v[104:105], v[108:109]
	v_add_f32_e32 v108, 1.0, v110
	v_add_f32_e32 v109, 1.0, v111
	v_rcp_f32_e32 v108, v108
	v_rcp_f32_e32 v109, v109
	v_pk_mul_f32 v[104:105], v[96:97], v[104:105]
	v_pk_mul_f32 v[96:97], v[98:99], v[120:121] op_sel_hi:[1,0]
	v_pk_mul_f32 v[98:99], v[106:107], v[108:109]
; __device__ __forceinline__ float sigm(float x) { return __builtin_amdgcn_rcpf(1.0f + __expf(-x)); }
; __device__ __forceinline__ u32x4 pack8_bf16(const float (&o)[8]) { u32x4 w; w.x = cvt_pk_bf16(o[0], o[1]); w.y = cvt_pk_bf16(o[2], o[3]); w.z = cvt_pk_bf16(o[4], o[5]); w.w = cvt_pk_bf16(o[6], o[7]); return w; }
;     __device__ __forceinline__ void operator()(const f32x4 (&acc)[2][2][4][2], const Unit& u, int wr, int wc, int fr, int fq) const {
;     ...
;         for (int ai = 0; ai < 2; ++ai)
; #pragma unroll
;             for (int m = 0; m < 4; ++m) {
;                 const int row = row0 + ai * HALF + m * 16;
;                 float ss = (sq[ai][m][0] + sq[ai][m][1]) + (sq[ai][m][2] + sq[ai][m][3]);
;                 ss += __shfl_xor(ss, 16); ss += __shfl_xor(ss, 32);
;                 const float rstd = __builtin_amdgcn_rsqf(ss * (1.0f / 1024.0f) + 1e-6f);
;                 float o[8];
; #pragma unroll
;                 for (int k = 0; k < 8; ++k) { const float g = acc[ai][0][m][k >> 2][k & 3] * rstd, up = acc[ai][1][m][k >> 2][k & 3] * rstd; o[k] = g * sigm(g) * up; }
;                 *(u32x4*)(ACT + (size_t)row * 2816 + u.pn * 128 + wc * 32 + 8 * fq) = pack8_bf16(o);
;             }
	v_pk_mul_f32 v[106:107], v[96:97], v[98:99]
	v_cvt_pk_bf16_f32 v96, v100, v101
	v_cvt_pk_bf16_f32 v98, v104, v105
	v_cvt_pk_bf16_f32 v97, v102, v103
	v_mov_b32_e32 v100, v238
	v_mad_i64_i32 v[102:103], s[24:25], v184, s49, v[112:113]
	v_lshl_add_u64 v[102:103], v[102:103], 0, s[22:23]
	v_pk_mul_f32 v[92:93], v[92:93], v[100:101] op_sel_hi:[1,0]
	v_lshl_add_u64 v[102:103], v[102:103], 0, s[4:5]
	v_mul_f32_e32 v101, 0xbfb8aa3b, v92
	v_exp_f32_e32 v101, v101
	v_mul_f32_e32 v104, 0xbfb8aa3b, v93
	v_exp_f32_e32 v105, v104
	v_cvt_pk_bf16_f32 v99, v106, v107
	v_add_f32_e32 v101, 1.0, v101
	v_rcp_f32_e32 v104, v101
	v_add_f32_e32 v101, 1.0, v105
	v_rcp_f32_e32 v105, v101
	v_lshl_add_u64 v[102:103], v[102:103], 0, v[160:161]
	v_pk_mul_f32 v[94:95], v[94:95], v[100:101] op_sel_hi:[1,0]
	global_store_dwordx4 v[102:103], v[96:99], off
	v_pk_mul_f32 v[88:89], v[88:89], v[100:101] op_sel_hi:[1,0]
	v_pk_mul_f32 v[92:93], v[92:93], v[104:105]
	v_mul_f32_e32 v96, 0xbfb8aa3b, v94
	v_exp_f32_e32 v96, v96
	v_pk_mul_f32 v[88:89], v[88:89], v[92:93]
	v_mul_f32_e32 v92, 0xbfb8aa3b, v95
	v_exp_f32_e32 v93, v92
	v_pk_mul_f32 v[84:85], v[84:85], v[100:101] op_sel_hi:[1,0]
	v_add_f32_e32 v92, 1.0, v96
	v_mul_f32_e32 v96, 0xbfb8aa3b, v84
	v_mul_f32_e32 v97, 0xbfb8aa3b, v85
	v_exp_f32_e32 v96, v96
	v_exp_f32_e32 v97, v97
	v_add_f32_e32 v93, 1.0, v93
	v_rcp_f32_e32 v92, v92
	v_rcp_f32_e32 v93, v93
	v_add_f32_e32 v96, 1.0, v96
	v_add_f32_e32 v97, 1.0, v97
	v_rcp_f32_e32 v96, v96
	v_rcp_f32_e32 v97, v97
	v_pk_mul_f32 v[90:91], v[90:91], v[100:101] op_sel_hi:[1,0]
	v_pk_mul_f32 v[92:93], v[94:95], v[92:93]
	v_pk_mul_f32 v[86:87], v[86:87], v[100:101] op_sel_hi:[1,0]
	v_pk_mul_f32 v[90:91], v[90:91], v[92:93]
	v_mul_f32_e32 v92, 0xbfb8aa3b, v86
	v_pk_mul_f32 v[80:81], v[80:81], v[100:101] op_sel_hi:[1,0]
	v_pk_mul_f32 v[84:85], v[84:85], v[96:97]
	v_exp_f32_e32 v92, v92
	v_pk_mul_f32 v[84:85], v[80:81], v[84:85]
	v_mul_f32_e32 v80, 0xbfb8aa3b, v87
	v_exp_f32_e32 v81, v80
	v_add_f32_e32 v80, 1.0, v92
	v_add_f32_e32 v81, 1.0, v81
	v_rcp_f32_e32 v80, v80
	v_rcp_f32_e32 v81, v81
	v_pk_mul_f32 v[82:83], v[82:83], v[100:101] op_sel_hi:[1,0]
	v_pk_mul_f32 v[80:81], v[86:87], v[80:81]
	s_nop 0
	v_pk_mul_f32 v[86:87], v[82:83], v[80:81]
	v_cvt_pk_bf16_f32 v80, v88, v89
	v_cvt_pk_bf16_f32 v83, v86, v87
	v_cvt_pk_bf16_f32 v82, v84, v85
	v_mad_i64_i32 v[84:85], s[24:25], v182, s49, v[112:113]
	v_mov_b32_e32 v86, v239
	v_lshl_add_u64 v[84:85], v[84:85], 0, s[22:23]
	v_lshl_add_u64 v[84:85], v[84:85], 0, s[4:5]
	v_cvt_pk_bf16_f32 v81, v90, v91
	v_pk_mul_f32 v[76:77], v[76:77], v[86:87] op_sel_hi:[1,0]
	v_lshl_add_u64 v[84:85], v[84:85], 0, v[160:161]
	v_mul_f32_e32 v87, 0xbfb8aa3b, v76
	v_exp_f32_e32 v87, v87
	global_store_dwordx4 v[84:85], v[80:83], off
	v_pk_mul_f32 v[78:79], v[78:79], v[86:87] op_sel_hi:[1,0]
	s_nop 0
	v_mul_f32_e32 v80, 0xbfb8aa3b, v77
	v_exp_f32_e32 v81, v80
	v_mul_f32_e32 v82, 0xbfb8aa3b, v78
	v_mul_f32_e32 v83, 0xbfb8aa3b, v79
	v_exp_f32_e32 v82, v82
	v_exp_f32_e32 v83, v83
	v_add_f32_e32 v80, 1.0, v87
	v_add_f32_e32 v81, 1.0, v81
	v_rcp_f32_e32 v80, v80
	v_rcp_f32_e32 v81, v81
	v_add_f32_e32 v82, 1.0, v82
	v_add_f32_e32 v83, 1.0, v83
	v_rcp_f32_e32 v82, v82
	v_rcp_f32_e32 v83, v83
	v_pk_mul_f32 v[68:69], v[68:69], v[86:87] op_sel_hi:[1,0]
	v_pk_mul_f32 v[76:77], v[76:77], v[80:81]
	v_pk_mul_f32 v[70:71], v[70:71], v[86:87] op_sel_hi:[1,0]
	v_pk_mul_f32 v[68:69], v[68:69], v[76:77]
	v_pk_mul_f32 v[76:77], v[78:79], v[82:83]
	v_pk_mul_f32 v[72:73], v[72:73], v[86:87] op_sel_hi:[1,0]
	v_pk_mul_f32 v[70:71], v[70:71], v[76:77]
	v_mul_f32_e32 v78, 0xbfb8aa3b, v72
	v_mul_f32_e32 v76, 0xbfb8aa3b, v73
	v_exp_f32_e32 v78, v78
	v_exp_f32_e32 v77, v76
	v_pk_mul_f32 v[74:75], v[74:75], v[86:87] op_sel_hi:[1,0]
	v_pk_mul_f32 v[64:65], v[64:65], v[86:87] op_sel_hi:[1,0]
	v_add_f32_e32 v76, 1.0, v78
	v_add_f32_e32 v77, 1.0, v77
	v_mul_f32_e32 v78, 0xbfb8aa3b, v74
	v_mul_f32_e32 v79, 0xbfb8aa3b, v75
	v_rcp_f32_e32 v76, v76
	v_rcp_f32_e32 v77, v77
	v_exp_f32_e32 v78, v78
	v_exp_f32_e32 v79, v79
	v_pk_mul_f32 v[72:73], v[72:73], v[76:77]
	v_add_f32_e32 v76, 1.0, v78
	v_add_f32_e32 v77, 1.0, v79
	v_rcp_f32_e32 v76, v76
	v_rcp_f32_e32 v77, v77
	v_pk_mul_f32 v[72:73], v[64:65], v[72:73]
	v_pk_mul_f32 v[64:65], v[66:67], v[86:87] op_sel_hi:[1,0]
	v_pk_mul_f32 v[66:67], v[74:75], v[76:77]
	v_pk_mul_f32 v[74:75], v[64:65], v[66:67]
	v_cvt_pk_bf16_f32 v64, v68, v69
	v_cvt_pk_bf16_f32 v66, v72, v73
	v_cvt_pk_bf16_f32 v65, v70, v71
	v_mov_b32_e32 v68, v240
	v_mad_i64_i32 v[70:71], s[24:25], v180, s49, v[112:113]
	v_lshl_add_u64 v[70:71], v[70:71], 0, s[22:23]
	v_pk_mul_f32 v[60:61], v[60:61], v[68:69] op_sel_hi:[1,0]
	v_lshl_add_u64 v[70:71], v[70:71], 0, s[4:5]
	v_mul_f32_e32 v69, 0xbfb8aa3b, v60
	v_exp_f32_e32 v69, v69
	v_mul_f32_e32 v72, 0xbfb8aa3b, v61
	v_exp_f32_e32 v73, v72
	v_cvt_pk_bf16_f32 v67, v74, v75
	v_add_f32_e32 v69, 1.0, v69
	v_rcp_f32_e32 v72, v69
	v_add_f32_e32 v69, 1.0, v73
	v_rcp_f32_e32 v73, v69
	v_lshl_add_u64 v[70:71], v[70:71], 0, v[160:161]
	v_pk_mul_f32 v[62:63], v[62:63], v[68:69] op_sel_hi:[1,0]
	global_store_dwordx4 v[70:71], v[64:67], off
	v_pk_mul_f32 v[56:57], v[56:57], v[68:69] op_sel_hi:[1,0]
	v_pk_mul_f32 v[60:61], v[60:61], v[72:73]
	v_mul_f32_e32 v64, 0xbfb8aa3b, v62
	v_exp_f32_e32 v64, v64
	v_pk_mul_f32 v[56:57], v[56:57], v[60:61]
	v_mul_f32_e32 v60, 0xbfb8aa3b, v63
	v_exp_f32_e32 v61, v60
	v_pk_mul_f32 v[52:53], v[52:53], v[68:69] op_sel_hi:[1,0]
	v_add_f32_e32 v60, 1.0, v64
	v_mul_f32_e32 v64, 0xbfb8aa3b, v52
	v_mul_f32_e32 v65, 0xbfb8aa3b, v53
	v_exp_f32_e32 v64, v64
	v_exp_f32_e32 v65, v65
	v_add_f32_e32 v61, 1.0, v61
	v_rcp_f32_e32 v60, v60
; __device__ __forceinline__ float sigm(float x) { return __builtin_amdgcn_rcpf(1.0f + __expf(-x)); }
; __device__ __forceinline__ u32x4 pack8_bf16(const float (&o)[8]) { u32x4 w; w.x = cvt_pk_bf16(o[0], o[1]); w.y = cvt_pk_bf16(o[2], o[3]); w.z = cvt_pk_bf16(o[4], o[5]); w.w = cvt_pk_bf16(o[6], o[7]); return w; }
;     __device__ __forceinline__ void operator()(const f32x4 (&acc)[2][2][4][2], const Unit& u, int wr, int wc, int fr, int fq) const {
;     ...
;         for (int ai = 0; ai < 2; ++ai)
; #pragma unroll
;             for (int m = 0; m < 4; ++m) {
;                 const int row = row0 + ai * HALF + m * 16;
;                 float ss = (sq[ai][m][0] + sq[ai][m][1]) + (sq[ai][m][2] + sq[ai][m][3]);
;                 ss += __shfl_xor(ss, 16); ss += __shfl_xor(ss, 32);
;                 const float rstd = __builtin_amdgcn_rsqf(ss * (1.0f / 1024.0f) + 1e-6f);
;                 float o[8];
; #pragma unroll
;                 for (int k = 0; k < 8; ++k) { const float g = acc[ai][0][m][k >> 2][k & 3] * rstd, up = acc[ai][1][m][k >> 2][k & 3] * rstd; o[k] = g * sigm(g) * up; }
;                 *(u32x4*)(ACT + (size_t)row * 2816 + u.pn * 128 + wc * 32 + 8 * fq) = pack8_bf16(o);
;             }
	v_rcp_f32_e32 v61, v61
	v_add_f32_e32 v64, 1.0, v64
	v_add_f32_e32 v65, 1.0, v65
	v_rcp_f32_e32 v64, v64
	v_rcp_f32_e32 v65, v65
	v_pk_mul_f32 v[58:59], v[58:59], v[68:69] op_sel_hi:[1,0]
	v_pk_mul_f32 v[60:61], v[62:63], v[60:61]
	v_pk_mul_f32 v[54:55], v[54:55], v[68:69] op_sel_hi:[1,0]
	v_pk_mul_f32 v[58:59], v[58:59], v[60:61]
	v_mul_f32_e32 v60, 0xbfb8aa3b, v54
	v_pk_mul_f32 v[48:49], v[48:49], v[68:69] op_sel_hi:[1,0]
	v_pk_mul_f32 v[52:53], v[52:53], v[64:65]
	v_exp_f32_e32 v60, v60
	v_pk_mul_f32 v[52:53], v[48:49], v[52:53]
	v_mul_f32_e32 v48, 0xbfb8aa3b, v55
	v_exp_f32_e32 v49, v48
	v_add_f32_e32 v48, 1.0, v60
	v_add_f32_e32 v49, 1.0, v49
	v_rcp_f32_e32 v48, v48
	v_rcp_f32_e32 v49, v49
	v_pk_mul_f32 v[50:51], v[50:51], v[68:69] op_sel_hi:[1,0]
	v_pk_mul_f32 v[48:49], v[54:55], v[48:49]
	s_nop 0
	v_pk_mul_f32 v[54:55], v[50:51], v[48:49]
	v_cvt_pk_bf16_f32 v48, v56, v57
	v_cvt_pk_bf16_f32 v51, v54, v55
	v_cvt_pk_bf16_f32 v50, v52, v53
	v_mad_i64_i32 v[52:53], s[24:25], v178, s49, v[112:113]
	v_mov_b32_e32 v54, v241
	v_lshl_add_u64 v[52:53], v[52:53], 0, s[22:23]
	v_lshl_add_u64 v[52:53], v[52:53], 0, s[4:5]
	v_cvt_pk_bf16_f32 v49, v58, v59
	v_pk_mul_f32 v[44:45], v[44:45], v[54:55] op_sel_hi:[1,0]
	v_lshl_add_u64 v[52:53], v[52:53], 0, v[160:161]
	v_mul_f32_e32 v55, 0xbfb8aa3b, v44
	v_exp_f32_e32 v55, v55
	global_store_dwordx4 v[52:53], v[48:51], off
	v_pk_mul_f32 v[46:47], v[46:47], v[54:55] op_sel_hi:[1,0]
	s_nop 0
	v_mul_f32_e32 v48, 0xbfb8aa3b, v45
	v_exp_f32_e32 v49, v48
	v_mul_f32_e32 v50, 0xbfb8aa3b, v46
	v_mul_f32_e32 v51, 0xbfb8aa3b, v47
	v_exp_f32_e32 v50, v50
	v_exp_f32_e32 v51, v51
	v_add_f32_e32 v48, 1.0, v55
	v_add_f32_e32 v49, 1.0, v49
	v_rcp_f32_e32 v48, v48
	v_rcp_f32_e32 v49, v49
	v_add_f32_e32 v50, 1.0, v50
	v_add_f32_e32 v51, 1.0, v51
	v_rcp_f32_e32 v50, v50
	v_rcp_f32_e32 v51, v51
	v_pk_mul_f32 v[36:37], v[36:37], v[54:55] op_sel_hi:[1,0]
	v_pk_mul_f32 v[44:45], v[44:45], v[48:49]
	v_pk_mul_f32 v[38:39], v[38:39], v[54:55] op_sel_hi:[1,0]
	v_pk_mul_f32 v[36:37], v[36:37], v[44:45]
	v_pk_mul_f32 v[44:45], v[46:47], v[50:51]
	v_pk_mul_f32 v[40:41], v[40:41], v[54:55] op_sel_hi:[1,0]
	v_pk_mul_f32 v[38:39], v[38:39], v[44:45]
	v_mul_f32_e32 v46, 0xbfb8aa3b, v40
	v_mul_f32_e32 v44, 0xbfb8aa3b, v41
	v_exp_f32_e32 v46, v46
	v_exp_f32_e32 v45, v44
	v_pk_mul_f32 v[42:43], v[42:43], v[54:55] op_sel_hi:[1,0]
	v_pk_mul_f32 v[32:33], v[32:33], v[54:55] op_sel_hi:[1,0]
	v_add_f32_e32 v44, 1.0, v46
	v_add_f32_e32 v45, 1.0, v45
	v_mul_f32_e32 v46, 0xbfb8aa3b, v42
	v_mul_f32_e32 v47, 0xbfb8aa3b, v43
	v_rcp_f32_e32 v44, v44
	v_rcp_f32_e32 v45, v45
	v_exp_f32_e32 v46, v46
	v_exp_f32_e32 v47, v47
	v_pk_mul_f32 v[40:41], v[40:41], v[44:45]
	v_add_f32_e32 v44, 1.0, v46
	v_add_f32_e32 v45, 1.0, v47
	v_rcp_f32_e32 v44, v44
	v_rcp_f32_e32 v45, v45
	v_pk_mul_f32 v[40:41], v[32:33], v[40:41]
	v_pk_mul_f32 v[32:33], v[34:35], v[54:55] op_sel_hi:[1,0]
	v_pk_mul_f32 v[34:35], v[42:43], v[44:45]
	v_pk_mul_f32 v[42:43], v[32:33], v[34:35]
	v_cvt_pk_bf16_f32 v32, v36, v37
	v_cvt_pk_bf16_f32 v34, v40, v41
	v_cvt_pk_bf16_f32 v33, v38, v39
	v_mov_b32_e32 v36, v242
	v_mad_i64_i32 v[38:39], s[24:25], v176, s49, v[112:113]
	v_lshl_add_u64 v[38:39], v[38:39], 0, s[22:23]
	v_pk_mul_f32 v[28:29], v[28:29], v[36:37] op_sel_hi:[1,0]
	v_lshl_add_u64 v[38:39], v[38:39], 0, s[4:5]
	v_mul_f32_e32 v37, 0xbfb8aa3b, v28
	v_exp_f32_e32 v37, v37
	v_mul_f32_e32 v40, 0xbfb8aa3b, v29
	v_exp_f32_e32 v41, v40
	v_cvt_pk_bf16_f32 v35, v42, v43
	v_add_f32_e32 v37, 1.0, v37
	v_rcp_f32_e32 v40, v37
	v_add_f32_e32 v37, 1.0, v41
	v_rcp_f32_e32 v41, v37
	v_lshl_add_u64 v[38:39], v[38:39], 0, v[160:161]
	v_pk_mul_f32 v[30:31], v[30:31], v[36:37] op_sel_hi:[1,0]
	global_store_dwordx4 v[38:39], v[32:35], off
	v_pk_mul_f32 v[24:25], v[24:25], v[36:37] op_sel_hi:[1,0]
	v_pk_mul_f32 v[28:29], v[28:29], v[40:41]
; __device__ __forceinline__ float sigm(float x) { return __builtin_amdgcn_rcpf(1.0f + __expf(-x)); }
; __device__ __forceinline__ u32x4 pack8_bf16(const float (&o)[8]) { u32x4 w; w.x = cvt_pk_bf16(o[0], o[1]); w.y = cvt_pk_bf16(o[2], o[3]); w.z = cvt_pk_bf16(o[4], o[5]); w.w = cvt_pk_bf16(o[6], o[7]); return w; }
;     __device__ __forceinline__ void operator()(const f32x4 (&acc)[2][2][4][2], const Unit& u, int wr, int wc, int fr, int fq) const {
;     ...
;         for (int ai = 0; ai < 2; ++ai)
; #pragma unroll
;             for (int m = 0; m < 4; ++m) {
;                 const int row = row0 + ai * HALF + m * 16;
;                 float ss = (sq[ai][m][0] + sq[ai][m][1]) + (sq[ai][m][2] + sq[ai][m][3]);
;                 ss += __shfl_xor(ss, 16); ss += __shfl_xor(ss, 32);
;                 const float rstd = __builtin_amdgcn_rsqf(ss * (1.0f / 1024.0f) + 1e-6f);
;                 float o[8];
; #pragma unroll
;                 for (int k = 0; k < 8; ++k) { const float g = acc[ai][0][m][k >> 2][k & 3] * rstd, up = acc[ai][1][m][k >> 2][k & 3] * rstd; o[k] = g * sigm(g) * up; }
;                 *(u32x4*)(ACT + (size_t)row * 2816 + u.pn * 128 + wc * 32 + 8 * fq) = pack8_bf16(o);
;             }
	v_mul_f32_e32 v32, 0xbfb8aa3b, v30
	v_exp_f32_e32 v32, v32
	v_pk_mul_f32 v[24:25], v[24:25], v[28:29]
	v_mul_f32_e32 v28, 0xbfb8aa3b, v31
	v_exp_f32_e32 v29, v28
	v_pk_mul_f32 v[20:21], v[20:21], v[36:37] op_sel_hi:[1,0]
	v_add_f32_e32 v28, 1.0, v32
	v_mul_f32_e32 v32, 0xbfb8aa3b, v20
	v_mul_f32_e32 v33, 0xbfb8aa3b, v21
	v_exp_f32_e32 v32, v32
	v_exp_f32_e32 v33, v33
	v_add_f32_e32 v29, 1.0, v29
	v_rcp_f32_e32 v28, v28
	v_rcp_f32_e32 v29, v29
	v_add_f32_e32 v32, 1.0, v32
	v_add_f32_e32 v33, 1.0, v33
	v_rcp_f32_e32 v32, v32
	v_rcp_f32_e32 v33, v33
	v_pk_mul_f32 v[26:27], v[26:27], v[36:37] op_sel_hi:[1,0]
	v_pk_mul_f32 v[28:29], v[30:31], v[28:29]
	v_pk_mul_f32 v[22:23], v[22:23], v[36:37] op_sel_hi:[1,0]
	v_pk_mul_f32 v[26:27], v[26:27], v[28:29]
	v_mul_f32_e32 v28, 0xbfb8aa3b, v22
	v_pk_mul_f32 v[16:17], v[16:17], v[36:37] op_sel_hi:[1,0]
	v_pk_mul_f32 v[20:21], v[20:21], v[32:33]
	v_exp_f32_e32 v28, v28
	v_pk_mul_f32 v[20:21], v[16:17], v[20:21]
	v_mul_f32_e32 v16, 0xbfb8aa3b, v23
	v_exp_f32_e32 v17, v16
	v_add_f32_e32 v16, 1.0, v28
	v_add_f32_e32 v17, 1.0, v17
	v_rcp_f32_e32 v16, v16
	v_rcp_f32_e32 v17, v17
	v_pk_mul_f32 v[18:19], v[18:19], v[36:37] op_sel_hi:[1,0]
	v_pk_mul_f32 v[16:17], v[22:23], v[16:17]
	s_nop 0
	v_pk_mul_f32 v[22:23], v[18:19], v[16:17]
	v_cvt_pk_bf16_f32 v16, v24, v25
	v_cvt_pk_bf16_f32 v19, v22, v23
	v_cvt_pk_bf16_f32 v18, v20, v21
	v_mad_i64_i32 v[20:21], s[24:25], v174, s49, v[112:113]
	v_mov_b32_e32 v22, v243
	v_lshl_add_u64 v[20:21], v[20:21], 0, s[22:23]
	v_lshl_add_u64 v[20:21], v[20:21], 0, s[4:5]
	v_cvt_pk_bf16_f32 v17, v26, v27
	v_pk_mul_f32 v[12:13], v[12:13], v[22:23] op_sel_hi:[1,0]
	v_lshl_add_u64 v[20:21], v[20:21], 0, v[160:161]
	v_mul_f32_e32 v23, 0xbfb8aa3b, v12
	v_exp_f32_e32 v23, v23
	global_store_dwordx4 v[20:21], v[16:19], off
	v_pk_mul_f32 v[14:15], v[14:15], v[22:23] op_sel_hi:[1,0]
	s_nop 0
	v_mul_f32_e32 v16, 0xbfb8aa3b, v13
	v_exp_f32_e32 v17, v16
	v_mul_f32_e32 v18, 0xbfb8aa3b, v14
	v_mul_f32_e32 v19, 0xbfb8aa3b, v15
	v_exp_f32_e32 v18, v18
	v_exp_f32_e32 v19, v19
	v_add_f32_e32 v16, 1.0, v23
	v_add_f32_e32 v17, 1.0, v17
	v_rcp_f32_e32 v16, v16
	v_rcp_f32_e32 v17, v17
	v_add_f32_e32 v18, 1.0, v18
	v_add_f32_e32 v19, 1.0, v19
	v_rcp_f32_e32 v18, v18
	v_rcp_f32_e32 v19, v19
	v_pk_mul_f32 v[4:5], v[4:5], v[22:23] op_sel_hi:[1,0]
	v_pk_mul_f32 v[12:13], v[12:13], v[16:17]
	v_pk_mul_f32 v[8:9], v[8:9], v[22:23] op_sel_hi:[1,0]
	v_pk_mul_f32 v[4:5], v[4:5], v[12:13]
	v_pk_mul_f32 v[12:13], v[14:15], v[18:19]
	v_mul_f32_e32 v14, 0xbfb8aa3b, v8
	v_exp_f32_e32 v14, v14
	v_pk_mul_f32 v[6:7], v[6:7], v[22:23] op_sel_hi:[1,0]
	v_pk_mul_f32 v[10:11], v[10:11], v[22:23] op_sel_hi:[1,0]
	v_pk_mul_f32 v[6:7], v[6:7], v[12:13]
	v_mul_f32_e32 v12, 0xbfb8aa3b, v9
	v_exp_f32_e32 v13, v12
	v_add_f32_e32 v12, 1.0, v14
	v_mul_f32_e32 v14, 0xbfb8aa3b, v10
	v_mul_f32_e32 v15, 0xbfb8aa3b, v11
	v_exp_f32_e32 v14, v14
	v_exp_f32_e32 v15, v15
	v_add_f32_e32 v13, 1.0, v13
	v_rcp_f32_e32 v12, v12
	v_rcp_f32_e32 v13, v13
	v_add_f32_e32 v14, 1.0, v14
	v_add_f32_e32 v15, 1.0, v15
	v_rcp_f32_e32 v14, v14
	v_rcp_f32_e32 v15, v15
	v_pk_mul_f32 v[0:1], v[0:1], v[22:23] op_sel_hi:[1,0]
	v_pk_mul_f32 v[8:9], v[8:9], v[12:13]
	s_nop 0
	v_pk_mul_f32 v[8:9], v[0:1], v[8:9]
	v_pk_mul_f32 v[0:1], v[2:3], v[22:23] op_sel_hi:[1,0]
	v_pk_mul_f32 v[2:3], v[10:11], v[14:15]
	s_nop 0
	v_pk_mul_f32 v[10:11], v[0:1], v[2:3]
	v_cvt_pk_bf16_f32 v0, v4, v5
	v_mad_i64_i32 v[4:5], s[24:25], v172, s49, v[112:113]
	v_lshl_add_u64 v[4:5], v[4:5], 0, s[22:23]
	v_lshl_add_u64 v[4:5], v[4:5], 0, s[4:5]
	v_cvt_pk_bf16_f32 v1, v6, v7
	v_cvt_pk_bf16_f32 v2, v8, v9
	v_cvt_pk_bf16_f32 v3, v10, v11
	v_lshl_add_u64 v[4:5], v[4:5], 0, v[160:161]
	global_store_dwordx4 v[4:5], v[0:3], off
	s_cbranch_vccnz .LBB0_965
	s_andn2_b64 vcc, exec, s[6:7]
	s_cbranch_vccnz .LBB0_964
	s_barrier
	s_branch .LBB0_964
